# SWA bias+mask as straight-line code with hoisted LDS lookups (no exec branching)
# speedup vs baseline: 1.0070x; 1.0070x over previous
.LBB0_465:
	s_add_i32 s38, s21, s30
	s_cmp_gt_i32 s38, -1
	s_cselect_b64 s[30:31], -1, 0
	s_add_i32 s39, s34, s20
	s_add_i32 s40, s39, 63
	s_cmp_ge_i32 s40, s24
	s_cselect_b64 s[40:41], -1, 0
	s_and_b64 s[30:31], s[30:31], s[40:41]
	s_andn2_b64 vcc, exec, s[30:31]
	s_cbranch_vccnz .LBB0_534
	s_mul_hi_u32 s30, s28, 0xcccccccd
	s_lshr_b32 s40, s30, 2
	s_mul_i32 s30, s40, 0xb400
	v_subrev_u32_e32 v0, s30, v122
	v_add_u32_e32 v0, 0, v0
	ds_read_b128 v[10:13], v0
	ds_read_b128 v[130:133], v0 offset:32
	ds_read_b128 v[48:51], v0 offset:4608
	ds_read_b128 v[134:137], v0 offset:4640
	ds_read_b128 v[138:141], v0 offset:64
	ds_read_b128 v[142:145], v0 offset:96
	ds_read_b128 v[146:149], v0 offset:4672
	ds_read_b128 v[150:153], v0 offset:4704
	v_add_u32_e32 v242, 0x1ab54, v126
	ds_read_b32 v210, v124
	ds_read_b32 v211, v242 offset:108
	ds_read_b32 v212, v242 offset:232
	ds_read_b32 v213, v242 offset:104
	ds_read_b32 v214, v242 offset:228
	ds_read_b32 v215, v242 offset:100
	ds_read_b32 v216, v242 offset:224
	ds_read_b32 v217, v242 offset:96
	ds_read_b32 v218, v242 offset:204
	ds_read_b32 v219, v242 offset:76
	ds_read_b32 v220, v242 offset:200
	ds_read_b32 v221, v242 offset:72
	ds_read_b32 v222, v242 offset:196
	ds_read_b32 v223, v242 offset:68
	ds_read_b32 v224, v242 offset:192
	ds_read_b32 v225, v242 offset:64
	ds_read_b32 v226, v242 offset:172
	ds_read_b32 v227, v242 offset:44
	ds_read_b32 v228, v242 offset:168
	ds_read_b32 v229, v242 offset:40
	ds_read_b32 v230, v242 offset:164
	ds_read_b32 v231, v242 offset:36
	ds_read_b32 v232, v242 offset:160
	ds_read_b32 v233, v242 offset:32
	ds_read_b32 v234, v242 offset:140
	ds_read_b32 v235, v242 offset:12
	ds_read_b32 v236, v242 offset:136
	ds_read_b32 v237, v242 offset:8
	ds_read_b32 v238, v242 offset:132
	ds_read_b32 v239, v242 offset:4
	ds_read_b32 v240, v242 offset:128
	ds_read_b32 v241, v242 offset:0
	s_waitcnt lgkmcnt(15)
	v_mfma_f32_32x32x16_bf16 v[64:79], v[10:13], v[80:83], 0
	v_add_u32_e32 v0, 59, v123
	v_cmp_gt_u32_e32 vcc, s27, v0
	v_mov_b32_e32 v0, 0xff800000
	v_mov_b32_e32 v10, 0xff800000
	v_mfma_f32_32x32x16_bf16 v[48:63], v[48:51], v[80:83], 0
	v_mfma_f32_32x32x16_bf16 v[64:79], v[130:133], v[84:87], v[64:79]
	v_mfma_f32_32x32x16_bf16 v[48:63], v[134:137], v[84:87], v[48:63]
	v_mfma_f32_32x32x16_bf16 v[64:79], v[138:141], v[88:91], v[64:79]
	v_mfma_f32_32x32x16_bf16 v[48:63], v[146:149], v[88:91], v[48:63]
	v_mfma_f32_32x32x16_bf16 v[64:79], v[142:145], v[92:95], v[64:79]
	v_mfma_f32_32x32x16_bf16 v[48:63], v[150:153], v[92:95], v[48:63]
	s_waitcnt lgkmcnt(0)
	s_nop 11
	v_add_f32_e32 v210, v64, v210
	s_nop 0
	v_cndmask_b32_e32 v10, v10, v210, vcc
	v_add_u32_e32 v11, 27, v123
	v_cmp_gt_u32_e32 vcc, s27, v11
	v_add_u32_e32 v129, 0, v126
	v_add_f32_e32 v211, v48, v211
	s_nop 0
	v_cndmask_b32_e32 v0, v0, v211, vcc
	v_add_u32_e32 v11, s34, v127
	v_cmp_lt_u32_e32 vcc, s47, v11
	v_mov_b32_e32 v11, 0xff800000
	v_mov_b32_e32 v12, 0xff800000
	v_add_f32_e32 v212, v65, v212
	s_nop 0
	v_cndmask_b32_e32 v12, v12, v212, vcc
	v_add_u32_e32 v13, 26, v123
	v_cmp_gt_u32_e32 vcc, s27, v13
	v_add_f32_e32 v213, v49, v213
	s_nop 0
	v_cndmask_b32_e32 v11, v11, v213, vcc
	v_add_u32_e32 v13, 57, v123
	v_cmp_gt_u32_e32 vcc, s27, v13
	v_mov_b32_e32 v13, 0xff800000
	v_mov_b32_e32 v14, 0xff800000
	v_add_f32_e32 v214, v66, v214
	s_nop 0
	v_cndmask_b32_e32 v14, v14, v214, vcc
	v_add_u32_e32 v15, 25, v123
	v_cmp_gt_u32_e32 vcc, s27, v15
	v_add_f32_e32 v215, v50, v215
	s_nop 0
	v_cndmask_b32_e32 v13, v13, v215, vcc
	v_add_u32_e32 v15, 56, v123
	v_cmp_gt_u32_e32 vcc, s27, v15
	v_mov_b32_e32 v15, 0xff800000
	v_mov_b32_e32 v48, 0xff800000
	v_add_f32_e32 v216, v67, v216
	s_nop 0
	v_cndmask_b32_e32 v48, v48, v216, vcc
	v_add_u32_e32 v49, 24, v123
	v_cmp_gt_u32_e32 vcc, s27, v49
	v_add_f32_e32 v217, v51, v217
	s_nop 0
	v_cndmask_b32_e32 v15, v15, v217, vcc
	v_add_u32_e32 v49, 51, v123
	v_cmp_gt_u32_e32 vcc, s27, v49
	v_mov_b32_e32 v49, 0xff800000
	v_mov_b32_e32 v50, 0xff800000
	v_add_f32_e32 v218, v68, v218
	s_nop 0
	v_cndmask_b32_e32 v50, v50, v218, vcc
	v_add_u32_e32 v51, 19, v123
	v_cmp_gt_u32_e32 vcc, s27, v51
	v_add_f32_e32 v219, v52, v219
	s_nop 0
	v_cndmask_b32_e32 v49, v49, v219, vcc
	v_add_u32_e32 v51, 50, v123
	v_cmp_gt_u32_e32 vcc, s27, v51
	v_mov_b32_e32 v52, 0xff800000
	v_mov_b32_e32 v64, 0xff800000
	v_add_f32_e32 v220, v69, v220
	s_nop 0
	v_cndmask_b32_e32 v64, v64, v220, vcc
	v_add_u32_e32 v51, 18, v123
	v_cmp_gt_u32_e32 vcc, s27, v51
	v_add_f32_e32 v221, v53, v221
	s_nop 0
	v_cndmask_b32_e32 v52, v52, v221, vcc
	v_add_u32_e32 v51, 49, v123
	v_cmp_gt_u32_e32 vcc, s27, v51
	v_mov_b32_e32 v53, 0xff800000
	v_mov_b32_e32 v65, 0xff800000
	v_add_f32_e32 v222, v70, v222
	s_nop 0
	v_cndmask_b32_e32 v65, v65, v222, vcc
	v_add_u32_e32 v51, 17, v123
	v_cmp_gt_u32_e32 vcc, s27, v51
	v_add_f32_e32 v223, v54, v223
	s_nop 0
	v_cndmask_b32_e32 v53, v53, v223, vcc
	v_add_u32_e32 v51, 48, v123
	v_cmp_gt_u32_e32 vcc, s27, v51
	v_mov_b32_e32 v54, 0xff800000
	v_mov_b32_e32 v66, 0xff800000
	v_add_f32_e32 v224, v71, v224
	s_nop 0
	v_cndmask_b32_e32 v66, v66, v224, vcc
	v_add_u32_e32 v51, 16, v123
	v_cmp_gt_u32_e32 vcc, s27, v51
	v_add_f32_e32 v225, v55, v225
	s_nop 0
	v_cndmask_b32_e32 v54, v54, v225, vcc
	v_add_u32_e32 v51, 43, v123
	v_cmp_gt_u32_e32 vcc, s27, v51
	v_mov_b32_e32 v55, 0xff800000
	v_mov_b32_e32 v67, 0xff800000
	v_add_f32_e32 v226, v72, v226
	s_nop 0
	v_cndmask_b32_e32 v67, v67, v226, vcc
	v_add_u32_e32 v51, 11, v123
	v_cmp_gt_u32_e32 vcc, s27, v51
	v_add_f32_e32 v227, v56, v227
	s_nop 0
	v_cndmask_b32_e32 v55, v55, v227, vcc
	v_add_u32_e32 v51, 42, v123
	v_cmp_gt_u32_e32 vcc, s27, v51
	v_mov_b32_e32 v56, 0xff800000
	v_mov_b32_e32 v68, 0xff800000
	v_add_f32_e32 v228, v73, v228
	s_nop 0
	v_cndmask_b32_e32 v68, v68, v228, vcc
	v_add_u32_e32 v51, 10, v123
	v_cmp_gt_u32_e32 vcc, s27, v51
	v_add_f32_e32 v229, v57, v229
	s_nop 0
	v_cndmask_b32_e32 v56, v56, v229, vcc
	v_add_u32_e32 v51, 41, v123
	v_cmp_gt_u32_e32 vcc, s27, v51
	v_mov_b32_e32 v57, 0xff800000
	v_mov_b32_e32 v69, 0xff800000
	v_add_f32_e32 v230, v74, v230
	s_nop 0
	v_cndmask_b32_e32 v69, v69, v230, vcc
	v_add_u32_e32 v51, 9, v123
	v_cmp_gt_u32_e32 vcc, s27, v51
	v_add_f32_e32 v231, v58, v231
	s_nop 0
	v_cndmask_b32_e32 v57, v57, v231, vcc
	v_add_u32_e32 v51, 40, v123
	v_cmp_gt_u32_e32 vcc, s27, v51
	v_mov_b32_e32 v58, 0xff800000
	v_mov_b32_e32 v70, 0xff800000
	v_add_f32_e32 v232, v75, v232
	s_nop 0
	v_cndmask_b32_e32 v70, v70, v232, vcc
	v_add_u32_e32 v51, 8, v123
	v_cmp_gt_u32_e32 vcc, s27, v51
	v_add_f32_e32 v233, v59, v233
	s_nop 0
	v_cndmask_b32_e32 v58, v58, v233, vcc
	v_add_u32_e32 v51, 35, v123
	v_cmp_gt_u32_e32 vcc, s27, v51
	v_mov_b32_e32 v59, 0xff800000
	v_mov_b32_e32 v71, 0xff800000
	v_add_f32_e32 v234, v76, v234
	s_nop 0
	v_cndmask_b32_e32 v71, v71, v234, vcc
	v_add_u32_e32 v51, 3, v123
	v_cmp_gt_u32_e32 vcc, s27, v51
	v_add_f32_e32 v235, v60, v235
	s_nop 0
	v_cndmask_b32_e32 v59, v59, v235, vcc
	v_add_u32_e32 v51, 34, v123
	v_cmp_gt_u32_e32 vcc, s27, v51
	v_mov_b32_e32 v60, 0xff800000
	v_mov_b32_e32 v72, 0xff800000
	v_add_f32_e32 v236, v77, v236
	s_nop 0
	v_cndmask_b32_e32 v72, v72, v236, vcc
	v_add_u32_e32 v51, 2, v123
	v_cmp_gt_u32_e32 vcc, s27, v51
	v_add_f32_e32 v237, v61, v237
	s_nop 0
	v_cndmask_b32_e32 v60, v60, v237, vcc
	v_add_u32_e32 v51, 33, v123
	v_cmp_gt_u32_e32 vcc, s27, v51
	v_mov_b32_e32 v61, 0xff800000
	v_mov_b32_e32 v73, 0xff800000
	v_add_f32_e32 v238, v78, v238
	s_nop 0
	v_cndmask_b32_e32 v73, v73, v238, vcc
	v_add_u32_e32 v51, 1, v123
	v_cmp_gt_u32_e32 vcc, s27, v51
	v_add_f32_e32 v239, v62, v239
	s_nop 0
	v_cndmask_b32_e32 v61, v61, v239, vcc
	v_add_u32_e32 v51, 32, v123
	v_cmp_gt_u32_e32 vcc, s27, v51
	v_mov_b32_e32 v62, 0xff800000
	v_mov_b32_e32 v74, 0xff800000
	v_add_f32_e32 v240, v79, v240
	s_nop 0
	v_cndmask_b32_e32 v74, v74, v240, vcc
	v_cmp_gt_u32_e32 vcc, s27, v123
	v_add_f32_e32 v241, v63, v241
	s_nop 0
	v_cndmask_b32_e32 v62, v62, v241, vcc
	v_max_f32_e32 v51, v13, v13
	v_max_f32_e32 v63, v14, v14
	v_max_f32_e32 v51, v63, v51
	v_max_f32_e32 v63, v49, v49
	v_max_f32_e32 v75, v50, v50
	v_max_f32_e32 v63, v75, v63
	v_max_f32_e32 v75, v52, v52
	v_max_f32_e32 v76, v64, v64
	v_max_f32_e32 v75, v76, v75
	v_max_f32_e32 v76, v53, v53
	v_max_f32_e32 v77, v65, v65
	v_max_f32_e32 v76, v77, v76
	v_max_f32_e32 v77, v54, v54
	v_max_f32_e32 v78, v66, v66
	v_max_f32_e32 v77, v78, v77
	v_max_f32_e32 v78, v55, v55
	v_max_f32_e32 v79, v67, v67
	v_max_f32_e32 v78, v79, v78
	v_max_f32_e32 v79, v56, v56
	v_max_f32_e32 v129, v68, v68
	v_max_f32_e32 v79, v129, v79
	v_max_f32_e32 v129, v57, v57
	v_max_f32_e32 v130, v69, v69
	v_max_f32_e32 v129, v130, v129
	v_max3_f32 v51, v51, v76, v129
	v_max_f32_e32 v76, v58, v58
	v_max_f32_e32 v129, v70, v70
	v_max_f32_e32 v76, v129, v76
	v_max_f32_e32 v129, v59, v59
	v_max_f32_e32 v130, v71, v71
	v_max3_f32 v63, v10, v0, v63
	v_max_f32_e32 v129, v130, v129
	v_max3_f32 v63, v63, v78, v129
	v_max_f32_e32 v78, v60, v60
	v_max_f32_e32 v129, v72, v72
	v_max3_f32 v75, v12, v11, v75
	v_max_f32_e32 v78, v129, v78
	v_max3_f32 v75, v75, v79, v78
	v_max_f32_e32 v78, v61, v61
	v_max_f32_e32 v79, v73, v73
	v_max_f32_e32 v78, v79, v78
	v_max_f32_e32 v79, v62, v62
	v_max_f32_e32 v129, v74, v74
	v_max3_f32 v77, v48, v15, v77
	v_max_f32_e32 v79, v129, v79
	v_max3_f32 v76, v77, v76, v79
	v_max3_f32 v51, v51, v78, v76
	v_max3_f32 v51, v63, v75, v51
	v_mov_b32_e32 v63, v51
	s_nop 1
	v_permlane32_swap_b32_e32 v51, v63
	v_max_f32_e32 v63, v63, v63
	v_max_f32_e32 v51, v51, v51
	v_max_f32_e32 v51, v51, v63
	v_add_f32_e32 v63, 0x41000000, v128
	v_cmp_gt_f32_e32 vcc, v51, v63
	s_cbranch_vccz .LBB0_535
	v_max_f32_e32 v51, v51, v51
	v_max_f32_e32 v63, v128, v128
	v_max_f32_e32 v51, v63, v51
	v_sub_f32_e32 v63, v128, v51
	v_exp_f32_e32 v63, v63
	s_and_saveexec_b64 s[30:31], s[4:5]
	ds_write_b32 v104, v63
	s_or_b64 exec, exec, s[30:31]
	ds_read_b128 v[76:79], v103
	ds_read_b128 v[128:131], v103 offset:32
	ds_read_b128 v[132:135], v103 offset:64
	ds_read_b128 v[136:139], v103 offset:96
	v_mul_f32_e32 v125, v125, v63
	s_waitcnt lgkmcnt(3)
	v_pk_mul_f32 v[34:35], v[34:35], v[78:79]
	s_waitcnt lgkmcnt(2)
	v_pk_mul_f32 v[38:39], v[38:39], v[130:131]
	s_waitcnt lgkmcnt(1)
	v_pk_mul_f32 v[42:43], v[42:43], v[134:135]
	s_waitcnt lgkmcnt(0)
	v_pk_mul_f32 v[46:47], v[46:47], v[138:139]
	v_pk_mul_f32 v[44:45], v[44:45], v[136:137]
	v_pk_mul_f32 v[40:41], v[40:41], v[132:133]
	v_pk_mul_f32 v[36:37], v[36:37], v[128:129]
	v_pk_mul_f32 v[32:33], v[32:33], v[76:77]
	v_pk_mul_f32 v[30:31], v[30:31], v[138:139]
	v_pk_mul_f32 v[26:27], v[26:27], v[134:135]
	v_pk_mul_f32 v[22:23], v[22:23], v[130:131]
	v_pk_mul_f32 v[18:19], v[18:19], v[78:79]
	v_pk_mul_f32 v[28:29], v[28:29], v[136:137]
	v_pk_mul_f32 v[24:25], v[24:25], v[132:133]
	v_pk_mul_f32 v[20:21], v[20:21], v[128:129]
	v_pk_mul_f32 v[16:17], v[16:17], v[76:77]
	s_branch .LBB0_536

.LBB0_551:
	s_add_i32 s28, s13, s29
	s_cmp_gt_i32 s28, -1
	s_cselect_b64 s[34:35], -1, 0
	s_add_i32 s29, s25, s15
	s_add_i32 s38, s29, 63
	s_cmp_ge_i32 s38, s16
	s_cselect_b64 s[38:39], -1, 0
	s_and_b64 s[34:35], s[34:35], s[38:39]
	s_andn2_b64 vcc, exec, s[34:35]
	s_cbranch_vccnz .LBB0_620
	s_mul_hi_u32 s34, s14, 0xcccccccd
	s_lshr_b32 s34, s34, 2
	s_mul_i32 s35, s34, 0xb400
	v_subrev_u32_e32 v0, s35, v123
	v_add_u32_e32 v0, 0, v0
	ds_read_b128 v[10:13], v0
	ds_read_b128 v[130:133], v0 offset:32
	ds_read_b128 v[48:51], v0 offset:4608
	ds_read_b128 v[134:137], v0 offset:4640
	ds_read_b128 v[138:141], v0 offset:64
	ds_read_b128 v[142:145], v0 offset:96
	ds_read_b128 v[146:149], v0 offset:4672
	ds_read_b128 v[150:153], v0 offset:4704
	v_add_u32_e32 v242, 0x1ab54, v126
	ds_read_b32 v210, v125
	ds_read_b32 v211, v242 offset:108
	ds_read_b32 v212, v242 offset:232
	ds_read_b32 v213, v242 offset:104
	ds_read_b32 v214, v242 offset:228
	ds_read_b32 v215, v242 offset:100
	ds_read_b32 v216, v242 offset:224
	ds_read_b32 v217, v242 offset:96
	ds_read_b32 v218, v242 offset:204
	ds_read_b32 v219, v242 offset:76
	ds_read_b32 v220, v242 offset:200
	ds_read_b32 v221, v242 offset:72
	ds_read_b32 v222, v242 offset:196
	ds_read_b32 v223, v242 offset:68
	ds_read_b32 v224, v242 offset:192
	ds_read_b32 v225, v242 offset:64
	ds_read_b32 v226, v242 offset:172
	ds_read_b32 v227, v242 offset:44
	ds_read_b32 v228, v242 offset:168
	ds_read_b32 v229, v242 offset:40
	ds_read_b32 v230, v242 offset:164
	ds_read_b32 v231, v242 offset:36
	ds_read_b32 v232, v242 offset:160
	ds_read_b32 v233, v242 offset:32
	ds_read_b32 v234, v242 offset:140
	ds_read_b32 v235, v242 offset:12
	ds_read_b32 v236, v242 offset:136
	ds_read_b32 v237, v242 offset:8
	ds_read_b32 v238, v242 offset:132
	ds_read_b32 v239, v242 offset:4
	ds_read_b32 v240, v242 offset:128
	ds_read_b32 v241, v242 offset:0
	s_waitcnt lgkmcnt(15)
	v_mfma_f32_32x32x16_bf16 v[64:79], v[10:13], v[80:83], 0
	v_add_u32_e32 v0, 59, v124
	v_cmp_gt_u32_e32 vcc, s27, v0
	v_mov_b32_e32 v0, 0xff800000
	v_mov_b32_e32 v10, 0xff800000
	v_mfma_f32_32x32x16_bf16 v[48:63], v[48:51], v[80:83], 0
	v_mfma_f32_32x32x16_bf16 v[64:79], v[130:133], v[84:87], v[64:79]
	v_mfma_f32_32x32x16_bf16 v[48:63], v[134:137], v[84:87], v[48:63]
	v_mfma_f32_32x32x16_bf16 v[64:79], v[138:141], v[88:91], v[64:79]
	v_mfma_f32_32x32x16_bf16 v[48:63], v[146:149], v[88:91], v[48:63]
	v_mfma_f32_32x32x16_bf16 v[64:79], v[142:145], v[92:95], v[64:79]
	v_mfma_f32_32x32x16_bf16 v[48:63], v[150:153], v[92:95], v[48:63]
	s_waitcnt lgkmcnt(0)
	s_nop 11
	v_add_f32_e32 v210, v64, v210
	s_nop 0
	v_cndmask_b32_e32 v10, v10, v210, vcc
	v_add_u32_e32 v11, 27, v124
	v_cmp_gt_u32_e32 vcc, s27, v11
	v_add_u32_e32 v130, 0, v126
	v_add_f32_e32 v211, v48, v211
	s_nop 0
	v_cndmask_b32_e32 v0, v0, v211, vcc
	v_add_u32_e32 v11, s25, v127
	v_cmp_lt_u32_e32 vcc, s47, v11
	v_mov_b32_e32 v11, 0xff800000
	v_mov_b32_e32 v12, 0xff800000
	v_add_f32_e32 v212, v65, v212
	s_nop 0
	v_cndmask_b32_e32 v12, v12, v212, vcc
	v_add_u32_e32 v13, 26, v124
	v_cmp_gt_u32_e32 vcc, s27, v13
	v_add_f32_e32 v213, v49, v213
	s_nop 0
	v_cndmask_b32_e32 v11, v11, v213, vcc
	v_add_u32_e32 v13, 57, v124
	v_cmp_gt_u32_e32 vcc, s27, v13
	v_mov_b32_e32 v13, 0xff800000
	v_mov_b32_e32 v14, 0xff800000
	v_add_f32_e32 v214, v66, v214
	s_nop 0
	v_cndmask_b32_e32 v14, v14, v214, vcc
	v_add_u32_e32 v15, 25, v124
	v_cmp_gt_u32_e32 vcc, s27, v15
	v_add_f32_e32 v215, v50, v215
	s_nop 0
	v_cndmask_b32_e32 v13, v13, v215, vcc
	v_add_u32_e32 v15, 56, v124
	v_cmp_gt_u32_e32 vcc, s27, v15
	v_mov_b32_e32 v15, 0xff800000
	v_mov_b32_e32 v48, 0xff800000
	v_add_f32_e32 v216, v67, v216
	s_nop 0
	v_cndmask_b32_e32 v48, v48, v216, vcc
	v_add_u32_e32 v49, 24, v124
	v_cmp_gt_u32_e32 vcc, s27, v49
	v_add_f32_e32 v217, v51, v217
	s_nop 0
	v_cndmask_b32_e32 v15, v15, v217, vcc
	v_add_u32_e32 v49, 51, v124
	v_cmp_gt_u32_e32 vcc, s27, v49
	v_mov_b32_e32 v49, 0xff800000
	v_mov_b32_e32 v50, 0xff800000
	v_add_f32_e32 v218, v68, v218
	s_nop 0
	v_cndmask_b32_e32 v50, v50, v218, vcc
	v_add_u32_e32 v51, 19, v124
	v_cmp_gt_u32_e32 vcc, s27, v51
	v_add_f32_e32 v219, v52, v219
	s_nop 0
	v_cndmask_b32_e32 v49, v49, v219, vcc
	v_add_u32_e32 v51, 50, v124
	v_cmp_gt_u32_e32 vcc, s27, v51
	v_mov_b32_e32 v52, 0xff800000
	v_mov_b32_e32 v64, 0xff800000
	v_add_f32_e32 v220, v69, v220
	s_nop 0
	v_cndmask_b32_e32 v64, v64, v220, vcc
	v_add_u32_e32 v51, 18, v124
	v_cmp_gt_u32_e32 vcc, s27, v51
	v_add_f32_e32 v221, v53, v221
	s_nop 0
	v_cndmask_b32_e32 v52, v52, v221, vcc
	v_add_u32_e32 v51, 49, v124
	v_cmp_gt_u32_e32 vcc, s27, v51
	v_mov_b32_e32 v53, 0xff800000
	v_mov_b32_e32 v65, 0xff800000
	v_add_f32_e32 v222, v70, v222
	s_nop 0
	v_cndmask_b32_e32 v65, v65, v222, vcc
	v_add_u32_e32 v51, 17, v124
	v_cmp_gt_u32_e32 vcc, s27, v51
	v_add_f32_e32 v223, v54, v223
	s_nop 0
	v_cndmask_b32_e32 v53, v53, v223, vcc
	v_add_u32_e32 v51, 48, v124
	v_cmp_gt_u32_e32 vcc, s27, v51
	v_mov_b32_e32 v54, 0xff800000
	v_mov_b32_e32 v66, 0xff800000
	v_add_f32_e32 v224, v71, v224
	s_nop 0
	v_cndmask_b32_e32 v66, v66, v224, vcc
	v_add_u32_e32 v51, 16, v124
	v_cmp_gt_u32_e32 vcc, s27, v51
	v_add_f32_e32 v225, v55, v225
	s_nop 0
	v_cndmask_b32_e32 v54, v54, v225, vcc
	v_add_u32_e32 v51, 43, v124
	v_cmp_gt_u32_e32 vcc, s27, v51
	v_mov_b32_e32 v55, 0xff800000
	v_mov_b32_e32 v67, 0xff800000
	v_add_f32_e32 v226, v72, v226
	s_nop 0
	v_cndmask_b32_e32 v67, v67, v226, vcc
	v_add_u32_e32 v51, 11, v124
	v_cmp_gt_u32_e32 vcc, s27, v51
	v_add_f32_e32 v227, v56, v227
	s_nop 0
	v_cndmask_b32_e32 v55, v55, v227, vcc
	v_add_u32_e32 v51, 42, v124
	v_cmp_gt_u32_e32 vcc, s27, v51
	v_mov_b32_e32 v56, 0xff800000
	v_mov_b32_e32 v68, 0xff800000
	v_add_f32_e32 v228, v73, v228
	s_nop 0
	v_cndmask_b32_e32 v68, v68, v228, vcc
	v_add_u32_e32 v51, 10, v124
	v_cmp_gt_u32_e32 vcc, s27, v51
	v_add_f32_e32 v229, v57, v229
	s_nop 0
	v_cndmask_b32_e32 v56, v56, v229, vcc
	v_add_u32_e32 v51, 41, v124
	v_cmp_gt_u32_e32 vcc, s27, v51
	v_mov_b32_e32 v57, 0xff800000
	v_mov_b32_e32 v69, 0xff800000
	v_add_f32_e32 v230, v74, v230
	s_nop 0
	v_cndmask_b32_e32 v69, v69, v230, vcc
	v_add_u32_e32 v51, 9, v124
	v_cmp_gt_u32_e32 vcc, s27, v51
	v_add_f32_e32 v231, v58, v231
	s_nop 0
	v_cndmask_b32_e32 v57, v57, v231, vcc
	v_add_u32_e32 v51, 40, v124
	v_cmp_gt_u32_e32 vcc, s27, v51
	v_mov_b32_e32 v58, 0xff800000
	v_mov_b32_e32 v70, 0xff800000
	v_add_f32_e32 v232, v75, v232
	s_nop 0
	v_cndmask_b32_e32 v70, v70, v232, vcc
	v_add_u32_e32 v51, 8, v124
	v_cmp_gt_u32_e32 vcc, s27, v51
	v_add_f32_e32 v233, v59, v233
	s_nop 0
	v_cndmask_b32_e32 v58, v58, v233, vcc
	v_add_u32_e32 v51, 35, v124
	v_cmp_gt_u32_e32 vcc, s27, v51
	v_mov_b32_e32 v59, 0xff800000
	v_mov_b32_e32 v71, 0xff800000
	v_add_f32_e32 v234, v76, v234
	s_nop 0
	v_cndmask_b32_e32 v71, v71, v234, vcc
	v_add_u32_e32 v51, 3, v124
	v_cmp_gt_u32_e32 vcc, s27, v51
	v_add_f32_e32 v235, v60, v235
	s_nop 0
	v_cndmask_b32_e32 v59, v59, v235, vcc
	v_add_u32_e32 v51, 34, v124
	v_cmp_gt_u32_e32 vcc, s27, v51
	v_mov_b32_e32 v60, 0xff800000
	v_mov_b32_e32 v72, 0xff800000
	v_add_f32_e32 v236, v77, v236
	s_nop 0
	v_cndmask_b32_e32 v72, v72, v236, vcc
	v_add_u32_e32 v51, 2, v124
	v_cmp_gt_u32_e32 vcc, s27, v51
	v_add_f32_e32 v237, v61, v237
	s_nop 0
	v_cndmask_b32_e32 v60, v60, v237, vcc
	v_add_u32_e32 v51, 33, v124
	v_cmp_gt_u32_e32 vcc, s27, v51
	v_mov_b32_e32 v61, 0xff800000
	v_mov_b32_e32 v73, 0xff800000
	v_add_f32_e32 v238, v78, v238
	s_nop 0
	v_cndmask_b32_e32 v73, v73, v238, vcc
	v_add_u32_e32 v51, 1, v124
	v_cmp_gt_u32_e32 vcc, s27, v51
	v_add_f32_e32 v239, v62, v239
	s_nop 0
	v_cndmask_b32_e32 v61, v61, v239, vcc
	v_add_u32_e32 v51, 32, v124
	v_cmp_gt_u32_e32 vcc, s27, v51
	v_mov_b32_e32 v62, 0xff800000
	v_mov_b32_e32 v74, 0xff800000
	v_add_f32_e32 v240, v79, v240
	s_nop 0
	v_cndmask_b32_e32 v74, v74, v240, vcc
	v_cmp_gt_u32_e32 vcc, s27, v124
	v_add_f32_e32 v241, v63, v241
	s_nop 0
	v_cndmask_b32_e32 v62, v62, v241, vcc
	v_max_f32_e32 v51, v13, v13
	v_max_f32_e32 v63, v14, v14
	v_max_f32_e32 v51, v63, v51
	v_max_f32_e32 v63, v49, v49
	v_max_f32_e32 v75, v50, v50
	v_max_f32_e32 v63, v75, v63
	v_max_f32_e32 v75, v52, v52
	v_max_f32_e32 v76, v64, v64
	v_max_f32_e32 v75, v76, v75
	v_max_f32_e32 v76, v53, v53
	v_max_f32_e32 v77, v65, v65
	v_max_f32_e32 v76, v77, v76
	v_max_f32_e32 v77, v54, v54
	v_max_f32_e32 v78, v66, v66
	v_max_f32_e32 v77, v78, v77
	v_max_f32_e32 v78, v55, v55
	v_max_f32_e32 v79, v67, v67
	v_max_f32_e32 v78, v79, v78
	v_max_f32_e32 v79, v56, v56
	v_max_f32_e32 v130, v68, v68
	v_max_f32_e32 v79, v130, v79
	v_max_f32_e32 v130, v57, v57
	v_max_f32_e32 v131, v69, v69
	v_max_f32_e32 v130, v131, v130
	v_max3_f32 v51, v51, v76, v130
	v_max_f32_e32 v76, v58, v58
	v_max_f32_e32 v130, v70, v70
	v_max_f32_e32 v76, v130, v76
	v_max_f32_e32 v130, v59, v59
	v_max_f32_e32 v131, v71, v71
	v_max3_f32 v63, v10, v0, v63
	v_max_f32_e32 v130, v131, v130
	v_max3_f32 v63, v63, v78, v130
	v_max_f32_e32 v78, v60, v60
	v_max_f32_e32 v130, v72, v72
	v_max3_f32 v75, v12, v11, v75
	v_max_f32_e32 v78, v130, v78
	v_max3_f32 v75, v75, v79, v78
	v_max_f32_e32 v78, v61, v61
	v_max_f32_e32 v79, v73, v73
	v_max_f32_e32 v78, v79, v78
	v_max_f32_e32 v79, v62, v62
	v_max_f32_e32 v130, v74, v74
	v_max3_f32 v77, v48, v15, v77
	v_max_f32_e32 v79, v130, v79
	v_max3_f32 v76, v77, v76, v79
	v_max3_f32 v51, v51, v78, v76
	v_max3_f32 v51, v63, v75, v51
	v_mov_b32_e32 v63, v51
	s_nop 1
	v_permlane32_swap_b32_e32 v51, v63
	v_max_f32_e32 v63, v63, v63
	v_max_f32_e32 v51, v51, v51
	v_max_f32_e32 v51, v51, v63
	v_add_f32_e32 v63, 0x41000000, v129
	v_cmp_gt_f32_e32 vcc, v51, v63
	s_cbranch_vccz .LBB0_621
	v_max_f32_e32 v51, v51, v51
	v_max_f32_e32 v63, v129, v129
	v_max_f32_e32 v51, v63, v51
	v_sub_f32_e32 v63, v129, v51
	v_exp_f32_e32 v63, v63
	s_and_saveexec_b64 s[38:39], s[6:7]
	ds_write_b32 v104, v63
	s_or_b64 exec, exec, s[38:39]
	ds_read_b128 v[76:79], v103
	ds_read_b128 v[130:133], v103 offset:32
	ds_read_b128 v[134:137], v103 offset:64
	ds_read_b128 v[138:141], v103 offset:96
	v_mul_f32_e32 v128, v128, v63
	s_waitcnt lgkmcnt(3)
	v_pk_mul_f32 v[34:35], v[34:35], v[78:79]
	s_waitcnt lgkmcnt(2)
	v_pk_mul_f32 v[38:39], v[38:39], v[132:133]
	s_waitcnt lgkmcnt(1)
	v_pk_mul_f32 v[42:43], v[42:43], v[136:137]
	s_waitcnt lgkmcnt(0)
	v_pk_mul_f32 v[46:47], v[46:47], v[140:141]
	v_pk_mul_f32 v[44:45], v[44:45], v[138:139]
	v_pk_mul_f32 v[40:41], v[40:41], v[134:135]
	v_pk_mul_f32 v[36:37], v[36:37], v[130:131]
	v_pk_mul_f32 v[32:33], v[32:33], v[76:77]
	v_pk_mul_f32 v[30:31], v[30:31], v[140:141]
	v_pk_mul_f32 v[26:27], v[26:27], v[136:137]
	v_pk_mul_f32 v[22:23], v[22:23], v[132:133]
	v_pk_mul_f32 v[18:19], v[18:19], v[78:79]
	v_pk_mul_f32 v[28:29], v[28:29], v[138:139]
	v_pk_mul_f32 v[24:25], v[24:25], v[134:135]
	v_pk_mul_f32 v[20:21], v[20:21], v[130:131]
	v_pk_mul_f32 v[16:17], v[16:17], v[76:77]
	s_branch .LBB0_622
